# static priority for the slot-0 wave of each SIMD in the attention/queue phase and both LayerNorm phases
# baseline (speedup 1.0000x reference)
.LBB0_212:
	s_or_b64 exec, exec, s[6:7]
	s_waitcnt vmcnt(0)
.LBB0_213:
	s_or_b64 exec, exec, s[2:3]
	s_waitcnt lgkmcnt(0)
	s_barrier
	s_setprio 0
.LBB0_214:
	s_mov_b64 s[0:1], 0
	v_writelane_b32 v255, s0, 22
	s_mov_b32 s74, 1
	s_and_b64 vcc, exec, s[8:9]
	v_writelane_b32 v255, s1, 23
	s_cbranch_vccz .LBB0_215
	s_getpc_b64 s[98:99]

.LBB0_961:
	v_readlane_b32 s0, v255, 26
	s_or_b32 s2, s0, 5
	v_readlane_b32 s4, v254, 3
	v_readlane_b32 s5, v254, 4
	s_cmp_le_i32 s4, s2
	s_cselect_b64 s[0:1], -1, 0
	s_cmp_lt_i32 s2, s5
	s_cselect_b64 s[2:3], -1, 0
	s_and_b64 s[0:1], s[0:1], s[2:3]
	s_andn2_b64 vcc, exec, s[0:1]
	s_cbranch_vccnz .LBB0_1027
	s_getreg_b32 s100, hwreg(HW_REG_HW_ID, 0, 4)
	s_cmp_lg_u32 s100, 0
	s_cbranch_scc1 .Lprio_done_ln1
	s_setprio 1
.Lprio_done_ln1:
	s_mov_b32 s2, s23
	s_getreg_b32 s0, hwreg(HW_REG_HW_ID, 0, 6)
	s_and_b32 s0, s0, 63
	s_lshl_b32 s0, s0, 2
	s_add_i32 s0, s0, 0
	s_add_i32 s0, s0, 0x20400
	v_mov_b32_e32 v0, s0
	ds_read_b32 v0, v0
	v_readlane_b32 s0, v254, 2
	v_mbcnt_lo_u32_b32 v90, -1, 0
	v_mbcnt_hi_u32_b32 v90, -1, v90
	s_and_b32 s4, s0, 7
	s_waitcnt lgkmcnt(0)
	v_readfirstlane_b32 s1, v0
	s_cmp_lg_u32 s4, 0
	s_nop 0
	v_lshl_add_u32 v0, s1, 6, v90
	s_mov_b32 s1, s92
	v_readfirstlane_b32 s3, v0
	s_cbranch_scc1 .LBB0_964
	s_ashr_i32 s5, s1, 31
	s_lshr_b32 s5, s5, 29
	s_add_i32 s5, s1, s5
	s_ashr_i32 s6, s5, 3
	s_and_b32 s5, s5, -8
	s_ashr_i32 s4, s0, 3
	s_sub_i32 s1, s1, s5
	s_mul_i32 s1, s1, s4
	s_add_i32 s1, s1, s6

.LBB0_1026:
	s_or_b64 exec, exec, s[2:3]
	s_waitcnt lgkmcnt(0)
	s_barrier
	s_setprio 0
.LBB0_1027:
	v_readlane_b32 s0, v255, 22
	v_readlane_b32 s1, v255, 23
	s_xor_b64 s[8:9], s[0:1], -1
	v_readlane_b32 s0, v255, 26
	s_or_b32 s2, s0, 6
	v_readlane_b32 s4, v254, 3
	v_readlane_b32 s5, v254, 4
	s_cmp_le_i32 s4, s2
	s_cselect_b64 s[0:1], -1, 0
	s_cmp_lt_i32 s2, s5
	s_cselect_b64 s[2:3], -1, 0
	s_and_b64 s[0:1], s[0:1], s[2:3]
	s_andn2_b64 vcc, exec, s[0:1]
	s_cbranch_vccnz .LBB0_1457
	s_mov_b32 s0, s23
	s_getreg_b32 s1, hwreg(HW_REG_HW_ID, 0, 6)
	s_and_b32 s1, s1, 63
	s_add_i32 s4, 0, 0x20400
	s_lshl_b32 s1, s1, 2
	s_add_i32 s1, s4, s1
	v_mov_b32_e32 v0, s1
	ds_read_b32 v0, v0
	v_mbcnt_lo_u32_b32 v193, -1, 0
	v_mbcnt_hi_u32_b32 v193, -1, v193
	v_readlane_b32 s19, v254, 2
	v_readlane_b32 s2, v254, 0
	s_waitcnt lgkmcnt(0)
	v_readfirstlane_b32 s1, v0
	s_mov_b32 s28, s92
	v_readlane_b32 s3, v254, 1
	v_lshl_add_u32 v0, s1, 6, v193
	s_mov_b32 s1, s92
	s_ashr_i32 s1, s0, 31
	s_lshl_b64 s[0:1], s[0:1], 3
	s_add_u32 s2, s2, s0
	s_getreg_b32 s0, hwreg(HW_REG_HW_ID, 0, 6)
	s_addc_u32 s3, s3, s1
	s_and_b32 s0, s0, 63
	s_lshl_b32 s0, s0, 2
	s_add_i32 s0, s4, s0
	v_readfirstlane_b32 s15, v0
	v_mov_b32_e32 v0, s0
	ds_read_b32 v0, v0
	v_mbcnt_lo_u32_b32 v11, -1, 0
	v_mbcnt_hi_u32_b32 v11, -1, v11
	s_cmpk_lt_i32 s28, 0x555
	s_cselect_b64 s[6:7], -1, 0
	s_cmpk_gt_i32 s28, 0x554
	s_waitcnt lgkmcnt(0)
	v_readfirstlane_b32 s0, v0
	s_nop 1
	v_lshl_add_u32 v0, s0, 6, v11
	s_nop 0
	v_readfirstlane_b32 s0, v0
	s_cbranch_scc1 .LBB0_1034
	s_ashr_i32 s1, s28, 31
	s_lshr_b32 s1, s1, 29
	s_add_i32 s1, s28, s1
	s_and_b32 s4, s1, -8
	s_sub_i32 s10, s28, s4
	s_cmp_gt_i32 s10, 4
	s_mov_b64 s[4:5], -1
	s_cbranch_scc0 .LBB0_1031
	s_mul_i32 s4, s10, 0xaa
	s_add_i32 s11, s4, 5
	s_mov_b64 s[4:5], 0

.LBB0_1600:
	s_getreg_b32 s100, hwreg(HW_REG_HW_ID, 0, 4)
	s_cmp_lg_u32 s100, 0
	s_cbranch_scc1 .Lprio_done_ln2
	s_setprio 1
